# v005 (setprio 1 before pre-MFMA barrier) + GU epilogue ssq loads prefetched after the last K-iteration wait
# speedup vs baseline: 1.0047x; 1.0047x over previous
; #define PG8_STAGE(bufoff, gbase, voff) do { _Pragma("unroll") for (int _i = 0; _i < 2; ++_i) \
;         __builtin_amdgcn_global_load_lds((const unsigned*)((const char*)(gbase) + (voff)[_i]), (PG8_LAS unsigned*)(lds + (bufoff) + ldsw + _i * 8192), 16, 0, 0); } while (0)
; #define PG8_LDA(dst, b, h) do { _Pragma("unroll") for (int m = 0; m < 4; ++m) _Pragma("unroll") for (int k = 0; k < 2; ++k) dst[m][k] = *(const PG8_LAS bf16x8*)(lds + PG8_SA(b, h) + aoff + m * 2048 + k * 1024); } while (0)
; #define PG8_LDB(dst, b, h) do { _Pragma("unroll") for (int n = 0; n < 2; ++n) _Pragma("unroll") for (int k = 0; k < 2; ++k) dst[n][k] = *(const PG8_LAS bf16x8*)(lds + PG8_SB(b, h) + boff + n * 2048 + k * 1024); } while (0)
; #define PG8_MMA(ai, bj, At, Bt) do { __builtin_amdgcn_s_setprio(1); _Pragma("unroll") for (int m = 0; m < 4; ++m) _Pragma("unroll") for (int n = 0; n < 2; ++n) _Pragma("unroll") for (int k = 0; k < 2; ++k) \
;         acc[ai][bj][m][n] = __builtin_amdgcn_mfma_f32_16x16x32_bf16(Bt[n][k], At[m][k], acc[ai][bj][m][n], 0, 0, 0); __builtin_amdgcn_s_setprio(0); } while (0)
; #define PG8_WAIT_V(n) asm volatile("s_waitcnt vmcnt(" #n ")" ::: "memory")
; #define PG8_BAR __builtin_amdgcn_s_barrier()
; template <class Epi, class Sched, bool ALIGN_EPI = false, bool SP2 = true>
; __device__ __forceinline__ void gemm_phase(PG8_LAS unsigned char* lds, const Gemm g, const Sched& S, const Epi& E) {
;     ...
;         for (int t = 0; t < nt; t += 2) {
;             const bool last = (t == nt - 2);
;             const char* a1 = cA + (size_t)(t + 1) * kstepA;
;             const char* a2 = last ? nA : cA + (size_t)(t + 2) * kstepA; const char* b2 = last ? nB : cB + (size_t)(t + 2) * kstep;
;             const char* a3 = a2 + kstepA; const char* b3 = b2 + kstep;
;             if (last && has_next) S.a_ready(nxt);
;             if constexpr (SP2) {
;             PG8_LDB(B0, 0, 0); PG8_LDB(B1, 0, 1); PG8_SCHED; PG8_LDA(At, 0, 0); PG8_STAGE(PG8_SA(1, 1), a1 + hstepA, voffA);
;             PG8_WAIT_V(8); PG8_WAIT_L(0); PG8_BAR; PG8_MMA(0, 0, At, B0); PG8_MMA(0, 1, At, B1); PG8_BAR; PG8_SCHED;
;             PG8_LDA(At, 0, 1); PG8_STAGE(PG8_SB(0, 0), b2, voffB); PG8_STAGE(PG8_SB(0, 1), b2 + hstep, voffB); PG8_STAGE(PG8_SA(0, 0), a2, voffA);
;             PG8_WAIT_V(8); PG8_WAIT_L(0); PG8_BAR; PG8_MMA(1, 0, At, B0); PG8_MMA(1, 1, At, B1); PG8_BAR; PG8_SCHED;
.LBB0_128:
	s_add_u32 s14, s46, 0xfffc0080
	s_addc_u32 s15, s47, -1
	s_add_i32 s70, 0, 0x10000
	s_cmp_eq_u32 s60, 12
	s_cselect_b32 s51, s17, s15
	s_cselect_b32 s50, s39, s14
	v_add_u32_e32 v141, s70, v147
	s_cselect_b32 s49, s25, s7
	s_cselect_b32 s48, s59, s6
	s_add_i32 s71, 0, 0x14000
	ds_read_b128 v[152:155], v141
	ds_read_b128 v[156:159], v141 offset:1024
	ds_read_b128 v[160:163], v141 offset:2048
	ds_read_b128 v[164:167], v141 offset:3072
	v_add_u32_e32 v141, s71, v147
	ds_read_b128 v[168:171], v141
	ds_read_b128 v[172:175], v141 offset:1024
	ds_read_b128 v[176:179], v141 offset:2048
	ds_read_b128 v[180:183], v141 offset:3072
	s_add_u32 s14, s6, 0x3ff80
	s_addc_u32 s15, s7, 0
	v_lshl_add_u64 v[148:149], s[14:15], 0, v[132:133]
	s_add_i32 m0, s28, 0x1c000
	ds_read_b128 v[184:187], v150
	ds_read_b128 v[188:191], v150 offset:1024
	ds_read_b128 v[200:203], v150 offset:2048
	ds_read_b128 v[204:207], v150 offset:3072
	ds_read_b128 v[208:211], v150 offset:4096
	ds_read_b128 v[212:215], v150 offset:5120
	ds_read_b128 v[216:219], v150 offset:6144
	ds_read_b128 v[220:223], v150 offset:7168
	global_load_lds_dwordx4 v[148:149], off
	v_lshl_add_u64 v[148:149], s[14:15], 0, v[128:129]
	s_add_i32 m0, s28, 0x1e000
	s_nop 0
	global_load_lds_dwordx4 v[148:149], off
	v_lshl_add_u64 v[148:149], s[46:47], 0, v[136:137]
	s_add_i32 m0, s29, 0xc000
	s_nop 0
	global_load_lds_dwordx4 v[148:149], off
	v_lshl_add_u64 v[148:149], s[46:47], 0, v[138:139]
	s_add_i32 m0, s29, 0xe000
	s_nop 0
	global_load_lds_dwordx4 v[148:149], off
	s_waitcnt vmcnt(8)
	s_waitcnt lgkmcnt(0)
	s_setprio 1
	s_barrier
	v_mfma_f32_16x16x32_bf16 v[120:123], v[152:155], v[184:187], v[120:123]
	v_mfma_f32_16x16x32_bf16 v[112:115], v[160:163], v[184:187], v[112:115]
	v_mfma_f32_16x16x32_bf16 v[108:111], v[152:155], v[200:203], v[108:111]
	v_mfma_f32_16x16x32_bf16 v[96:99], v[160:163], v[200:203], v[96:99]
	v_mfma_f32_16x16x32_bf16 v[92:95], v[152:155], v[208:211], v[92:95]
	v_mfma_f32_16x16x32_bf16 v[80:83], v[160:163], v[208:211], v[80:83]
	v_mfma_f32_16x16x32_bf16 v[76:79], v[152:155], v[216:219], v[76:79]
	v_mfma_f32_16x16x32_bf16 v[64:67], v[160:163], v[216:219], v[64:67]
	v_mfma_f32_16x16x32_bf16 v[120:123], v[156:159], v[188:191], v[120:123]
	v_mfma_f32_16x16x32_bf16 v[112:115], v[164:167], v[188:191], v[112:115]
	v_mfma_f32_16x16x32_bf16 v[108:111], v[156:159], v[204:207], v[108:111]
	v_mfma_f32_16x16x32_bf16 v[96:99], v[164:167], v[204:207], v[96:99]
	v_mfma_f32_16x16x32_bf16 v[92:95], v[156:159], v[212:215], v[92:95]
	v_mfma_f32_16x16x32_bf16 v[80:83], v[164:167], v[212:215], v[80:83]
	v_mfma_f32_16x16x32_bf16 v[76:79], v[156:159], v[220:223], v[76:79]
	v_mfma_f32_16x16x32_bf16 v[64:67], v[164:167], v[220:223], v[64:67]
	v_mfma_f32_16x16x32_bf16 v[124:127], v[168:171], v[184:187], v[124:127]
	v_mfma_f32_16x16x32_bf16 v[116:119], v[176:179], v[184:187], v[116:119]
	v_mfma_f32_16x16x32_bf16 v[104:107], v[168:171], v[200:203], v[104:107]
	v_mfma_f32_16x16x32_bf16 v[100:103], v[176:179], v[200:203], v[100:103]
	v_mfma_f32_16x16x32_bf16 v[88:91], v[168:171], v[208:211], v[88:91]
	v_mfma_f32_16x16x32_bf16 v[84:87], v[176:179], v[208:211], v[84:87]
	v_mfma_f32_16x16x32_bf16 v[72:75], v[168:171], v[216:219], v[72:75]
	v_mfma_f32_16x16x32_bf16 v[68:71], v[176:179], v[216:219], v[68:71]
	v_mfma_f32_16x16x32_bf16 v[124:127], v[172:175], v[188:191], v[124:127]
	v_mfma_f32_16x16x32_bf16 v[116:119], v[180:183], v[188:191], v[116:119]
	v_mfma_f32_16x16x32_bf16 v[104:107], v[172:175], v[204:207], v[104:107]
	v_mfma_f32_16x16x32_bf16 v[100:103], v[180:183], v[204:207], v[100:103]
	v_mfma_f32_16x16x32_bf16 v[88:91], v[172:175], v[212:215], v[88:91]
	v_mfma_f32_16x16x32_bf16 v[84:87], v[180:183], v[212:215], v[84:87]
	v_mfma_f32_16x16x32_bf16 v[72:75], v[172:175], v[220:223], v[72:75]
	v_mfma_f32_16x16x32_bf16 v[68:71], v[180:183], v[220:223], v[68:71]
	s_setprio 0
	s_barrier
	s_add_i32 s14, s70, s28
	v_lshl_add_u64 v[148:149], s[48:49], 0, v[132:133]
	s_mov_b32 m0, s14
	ds_read_b128 v[184:187], v150 offset:16384
	ds_read_b128 v[188:191], v150 offset:17408
	ds_read_b128 v[200:203], v150 offset:18432
	ds_read_b128 v[204:207], v150 offset:19456
	ds_read_b128 v[208:211], v150 offset:20480
	ds_read_b128 v[212:215], v150 offset:21504
	ds_read_b128 v[216:219], v150 offset:22528
	ds_read_b128 v[220:223], v150 offset:23552
	global_load_lds_dwordx4 v[148:149], off
	s_add_i32 m0, s14, 0x2000
	v_lshl_add_u64 v[224:225], s[48:49], 0, v[128:129]
	global_load_lds_dwordx4 v[224:225], off
	v_lshl_add_u64 v[234:235], s[50:51], 0, v[130:131]
	v_lshl_add_u64 v[226:227], s[50:51], 0, v[134:135]
	s_mov_b32 m0, s29
	s_nop 0
	global_load_lds_dwordx4 v[226:227], off
	s_mov_b32 m0, s30
	s_nop 0
	global_load_lds_dwordx4 v[234:235], off
	s_waitcnt vmcnt(6)
	s_waitcnt lgkmcnt(0)
	s_setprio 1
	s_barrier
; #define PG8_STAGE(bufoff, gbase, voff) do { _Pragma("unroll") for (int _i = 0; _i < 2; ++_i) \
;         __builtin_amdgcn_global_load_lds((const unsigned*)((const char*)(gbase) + (voff)[_i]), (PG8_LAS unsigned*)(lds + (bufoff) + ldsw + _i * 8192), 16, 0, 0); } while (0)
; #define PG8_LDA(dst, b, h) do { _Pragma("unroll") for (int m = 0; m < 4; ++m) _Pragma("unroll") for (int k = 0; k < 2; ++k) dst[m][k] = *(const PG8_LAS bf16x8*)(lds + PG8_SA(b, h) + aoff + m * 2048 + k * 1024); } while (0)
; #define PG8_LDB(dst, b, h) do { _Pragma("unroll") for (int n = 0; n < 2; ++n) _Pragma("unroll") for (int k = 0; k < 2; ++k) dst[n][k] = *(const PG8_LAS bf16x8*)(lds + PG8_SB(b, h) + boff + n * 2048 + k * 1024); } while (0)
; #define PG8_MMA(ai, bj, At, Bt) do { __builtin_amdgcn_s_setprio(1); _Pragma("unroll") for (int m = 0; m < 4; ++m) _Pragma("unroll") for (int n = 0; n < 2; ++n) _Pragma("unroll") for (int k = 0; k < 2; ++k) \
;         acc[ai][bj][m][n] = __builtin_amdgcn_mfma_f32_16x16x32_bf16(Bt[n][k], At[m][k], acc[ai][bj][m][n], 0, 0, 0); __builtin_amdgcn_s_setprio(0); } while (0)
; #define PG8_WAIT_V(n) asm volatile("s_waitcnt vmcnt(" #n ")" ::: "memory")
; #define PG8_WAIT_L(n) asm volatile("s_waitcnt lgkmcnt(" #n ")" ::: "memory")
; #define PG8_BAR __builtin_amdgcn_s_barrier()
; #define PG8_SCHED __builtin_amdgcn_sched_barrier(0)
; template <class Epi, class Sched, bool ALIGN_EPI = false, bool SP2 = true>
; __device__ __forceinline__ void gemm_phase(PG8_LAS unsigned char* lds, const Gemm g, const Sched& S, const Epi& E) {
;     ...
;             PG8_WAIT_V(8); PG8_WAIT_L(0); PG8_BAR; PG8_MMA(1, 0, At, B0); PG8_MMA(1, 1, At, B1); PG8_BAR; PG8_SCHED;
;             PG8_LDB(B0, 1, 0); PG8_LDB(B1, 1, 1); PG8_SCHED; PG8_LDA(At, 1, 0); PG8_STAGE(PG8_SA(0, 1), a2 + hstepA, voffA);
;             PG8_WAIT_V(8); PG8_WAIT_L(0); PG8_BAR; PG8_MMA(0, 0, At, B0); PG8_MMA(0, 1, At, B1); PG8_BAR; PG8_SCHED;
;             PG8_LDA(At, 1, 1); PG8_STAGE(PG8_SB(1, 0), b3, voffB); PG8_STAGE(PG8_SB(1, 1), b3 + hstep, voffB); PG8_STAGE(PG8_SA(1, 0), a3, voffA);
;             PG8_WAIT_V(8); PG8_WAIT_L(0); PG8_BAR; PG8_MMA(1, 0, At, B0); PG8_MMA(1, 1, At, B1); PG8_BAR; PG8_SCHED;
	v_mfma_f32_16x16x32_bf16 v[60:63], v[152:155], v[184:187], v[60:63]
	v_mfma_f32_16x16x32_bf16 v[48:51], v[160:163], v[184:187], v[48:51]
	v_mfma_f32_16x16x32_bf16 v[44:47], v[152:155], v[200:203], v[44:47]
	v_mfma_f32_16x16x32_bf16 v[32:35], v[160:163], v[200:203], v[32:35]
	v_mfma_f32_16x16x32_bf16 v[28:31], v[152:155], v[208:211], v[28:31]
	v_mfma_f32_16x16x32_bf16 v[16:19], v[160:163], v[208:211], v[16:19]
	v_mfma_f32_16x16x32_bf16 v[12:15], v[152:155], v[216:219], v[12:15]
	v_mfma_f32_16x16x32_bf16 v[4:7], v[160:163], v[216:219], v[4:7]
	v_mfma_f32_16x16x32_bf16 v[60:63], v[156:159], v[188:191], v[60:63]
	v_mfma_f32_16x16x32_bf16 v[48:51], v[164:167], v[188:191], v[48:51]
	v_mfma_f32_16x16x32_bf16 v[44:47], v[156:159], v[204:207], v[44:47]
	v_mfma_f32_16x16x32_bf16 v[32:35], v[164:167], v[204:207], v[32:35]
	v_mfma_f32_16x16x32_bf16 v[28:31], v[156:159], v[212:215], v[28:31]
	v_mfma_f32_16x16x32_bf16 v[16:19], v[164:167], v[212:215], v[16:19]
	v_mfma_f32_16x16x32_bf16 v[12:15], v[156:159], v[220:223], v[12:15]
	v_mfma_f32_16x16x32_bf16 v[4:7], v[164:167], v[220:223], v[4:7]
	v_mfma_f32_16x16x32_bf16 v[56:59], v[168:171], v[184:187], v[56:59]
	v_mfma_f32_16x16x32_bf16 v[52:55], v[176:179], v[184:187], v[52:55]
	v_mfma_f32_16x16x32_bf16 v[40:43], v[168:171], v[200:203], v[40:43]
	v_mfma_f32_16x16x32_bf16 v[36:39], v[176:179], v[200:203], v[36:39]
	v_mfma_f32_16x16x32_bf16 v[24:27], v[168:171], v[208:211], v[24:27]
	v_mfma_f32_16x16x32_bf16 v[20:23], v[176:179], v[208:211], v[20:23]
	v_mfma_f32_16x16x32_bf16 v[8:11], v[168:171], v[216:219], v[8:11]
	v_mfma_f32_16x16x32_bf16 v[0:3], v[176:179], v[216:219], v[0:3]
	v_mfma_f32_16x16x32_bf16 v[56:59], v[172:175], v[188:191], v[56:59]
	v_mfma_f32_16x16x32_bf16 v[52:55], v[180:183], v[188:191], v[52:55]
	v_mfma_f32_16x16x32_bf16 v[40:43], v[172:175], v[204:207], v[40:43]
	v_mfma_f32_16x16x32_bf16 v[36:39], v[180:183], v[204:207], v[36:39]
	v_mfma_f32_16x16x32_bf16 v[24:27], v[172:175], v[212:215], v[24:27]
	v_mfma_f32_16x16x32_bf16 v[20:23], v[180:183], v[212:215], v[20:23]
	v_mfma_f32_16x16x32_bf16 v[8:11], v[172:175], v[220:223], v[8:11]
	v_mfma_f32_16x16x32_bf16 v[0:3], v[180:183], v[220:223], v[0:3]
	s_setprio 0
	s_barrier
	s_add_i32 s70, 0, 0x18000
	v_add_u32_e32 v141, s70, v147
	s_add_i32 s71, 0, 0x1c000
	ds_read_b128 v[152:155], v141
	ds_read_b128 v[156:159], v141 offset:1024
	ds_read_b128 v[160:163], v141 offset:2048
	ds_read_b128 v[164:167], v141 offset:3072
	v_add_u32_e32 v141, s71, v147
	ds_read_b128 v[168:171], v141
	ds_read_b128 v[172:175], v141 offset:1024
	ds_read_b128 v[176:179], v141 offset:2048
	ds_read_b128 v[180:183], v141 offset:3072
	s_add_u32 s14, s48, 0x40000
	s_addc_u32 s15, s49, 0
	s_add_i32 m0, s28, 0x14000
	v_lshl_add_u64 v[236:237], s[14:15], 0, v[132:133]
	ds_read_b128 v[184:187], v150 offset:32768
	ds_read_b128 v[188:191], v150 offset:33792
	ds_read_b128 v[200:203], v150 offset:34816
	ds_read_b128 v[204:207], v150 offset:35840
	ds_read_b128 v[208:211], v150 offset:36864
	ds_read_b128 v[212:215], v150 offset:37888
	ds_read_b128 v[216:219], v150 offset:38912
	ds_read_b128 v[220:223], v150 offset:39936
	global_load_lds_dwordx4 v[236:237], off
	v_lshl_add_u64 v[236:237], s[14:15], 0, v[128:129]
	s_add_i32 m0, s28, 0x16000
	s_add_u32 s14, s50, 0x40000
	s_addc_u32 s15, s51, 0
	global_load_lds_dwordx4 v[236:237], off
	v_lshl_add_u64 v[236:237], s[14:15], 0, v[134:135]
	s_mov_b32 m0, s31
	s_nop 0
	global_load_lds_dwordx4 v[236:237], off
	v_lshl_add_u64 v[236:237], s[14:15], 0, v[130:131]
	s_mov_b32 m0, s34
	s_nop 0
	global_load_lds_dwordx4 v[236:237], off
	s_waitcnt vmcnt(8)
	s_waitcnt lgkmcnt(0)
	s_setprio 1
	s_barrier
	v_mfma_f32_16x16x32_bf16 v[120:123], v[152:155], v[184:187], v[120:123]
	v_mfma_f32_16x16x32_bf16 v[112:115], v[160:163], v[184:187], v[112:115]
	v_mfma_f32_16x16x32_bf16 v[108:111], v[152:155], v[200:203], v[108:111]
	v_mfma_f32_16x16x32_bf16 v[96:99], v[160:163], v[200:203], v[96:99]
	v_mfma_f32_16x16x32_bf16 v[92:95], v[152:155], v[208:211], v[92:95]
	v_mfma_f32_16x16x32_bf16 v[80:83], v[160:163], v[208:211], v[80:83]
	v_mfma_f32_16x16x32_bf16 v[76:79], v[152:155], v[216:219], v[76:79]
	v_mfma_f32_16x16x32_bf16 v[64:67], v[160:163], v[216:219], v[64:67]
	v_mfma_f32_16x16x32_bf16 v[120:123], v[156:159], v[188:191], v[120:123]
	v_mfma_f32_16x16x32_bf16 v[112:115], v[164:167], v[188:191], v[112:115]
	v_mfma_f32_16x16x32_bf16 v[108:111], v[156:159], v[204:207], v[108:111]
	v_mfma_f32_16x16x32_bf16 v[96:99], v[164:167], v[204:207], v[96:99]
	v_mfma_f32_16x16x32_bf16 v[92:95], v[156:159], v[212:215], v[92:95]
	v_mfma_f32_16x16x32_bf16 v[80:83], v[164:167], v[212:215], v[80:83]
	v_mfma_f32_16x16x32_bf16 v[76:79], v[156:159], v[220:223], v[76:79]
	v_mfma_f32_16x16x32_bf16 v[64:67], v[164:167], v[220:223], v[64:67]
	v_mfma_f32_16x16x32_bf16 v[124:127], v[168:171], v[184:187], v[124:127]
	v_mfma_f32_16x16x32_bf16 v[116:119], v[176:179], v[184:187], v[116:119]
	v_mfma_f32_16x16x32_bf16 v[104:107], v[168:171], v[200:203], v[104:107]
	v_mfma_f32_16x16x32_bf16 v[100:103], v[176:179], v[200:203], v[100:103]
	v_mfma_f32_16x16x32_bf16 v[88:91], v[168:171], v[208:211], v[88:91]
	v_mfma_f32_16x16x32_bf16 v[84:87], v[176:179], v[208:211], v[84:87]
	v_mfma_f32_16x16x32_bf16 v[72:75], v[168:171], v[216:219], v[72:75]
	v_mfma_f32_16x16x32_bf16 v[68:71], v[176:179], v[216:219], v[68:71]
	v_mfma_f32_16x16x32_bf16 v[124:127], v[172:175], v[188:191], v[124:127]
	v_mfma_f32_16x16x32_bf16 v[116:119], v[180:183], v[188:191], v[116:119]
	v_mfma_f32_16x16x32_bf16 v[104:107], v[172:175], v[204:207], v[104:107]
	v_mfma_f32_16x16x32_bf16 v[100:103], v[180:183], v[204:207], v[100:103]
	v_mfma_f32_16x16x32_bf16 v[88:91], v[172:175], v[212:215], v[88:91]
	v_mfma_f32_16x16x32_bf16 v[84:87], v[180:183], v[212:215], v[84:87]
	v_mfma_f32_16x16x32_bf16 v[72:75], v[172:175], v[220:223], v[72:75]
	v_mfma_f32_16x16x32_bf16 v[68:71], v[180:183], v[220:223], v[68:71]
	s_setprio 0
	s_barrier
; #define PG8_STAGE(bufoff, gbase, voff) do { _Pragma("unroll") for (int _i = 0; _i < 2; ++_i) \
;         __builtin_amdgcn_global_load_lds((const unsigned*)((const char*)(gbase) + (voff)[_i]), (PG8_LAS unsigned*)(lds + (bufoff) + ldsw + _i * 8192), 16, 0, 0); } while (0)
; #define PG8_LDA(dst, b, h) do { _Pragma("unroll") for (int m = 0; m < 4; ++m) _Pragma("unroll") for (int k = 0; k < 2; ++k) dst[m][k] = *(const PG8_LAS bf16x8*)(lds + PG8_SA(b, h) + aoff + m * 2048 + k * 1024); } while (0)
; #define PG8_MMA(ai, bj, At, Bt) do { __builtin_amdgcn_s_setprio(1); _Pragma("unroll") for (int m = 0; m < 4; ++m) _Pragma("unroll") for (int n = 0; n < 2; ++n) _Pragma("unroll") for (int k = 0; k < 2; ++k) \
;         acc[ai][bj][m][n] = __builtin_amdgcn_mfma_f32_16x16x32_bf16(Bt[n][k], At[m][k], acc[ai][bj][m][n], 0, 0, 0); __builtin_amdgcn_s_setprio(0); } while (0)
; #define PG8_WAIT_V(n) asm volatile("s_waitcnt vmcnt(" #n ")" ::: "memory")
; #define PG8_WAIT_L(n) asm volatile("s_waitcnt lgkmcnt(" #n ")" ::: "memory")
; #define PG8_BAR __builtin_amdgcn_s_barrier()
; #define PG8_SCHED __builtin_amdgcn_sched_barrier(0)
;     __device__ __forceinline__ void operator()(const f32x4 (&acc)[2][2][4][2], const Unit& u, int wr, int wc, int fr, int fq) const {
;     ...
;             for (int m = 0; m < 4; ++m) sv[ai][m] = ssq[row0 + ai * HALF + m * 16];
; template <class Epi, class Sched, bool ALIGN_EPI = false, bool SP2 = true>
; __device__ __forceinline__ void gemm_phase(PG8_LAS unsigned char* lds, const Gemm g, const Sched& S, const Epi& E) {
;     ...
;             PG8_LDA(At, 1, 1); PG8_STAGE(PG8_SB(1, 0), b3, voffB); PG8_STAGE(PG8_SB(1, 1), b3 + hstep, voffB); PG8_STAGE(PG8_SA(1, 0), a3, voffA);
;             PG8_WAIT_V(8); PG8_WAIT_L(0); PG8_BAR; PG8_MMA(1, 0, At, B0); PG8_MMA(1, 1, At, B1); PG8_BAR; PG8_SCHED;
	s_add_i32 s14, s70, s28
	v_lshl_add_u64 v[148:149], v[148:149], 0, s[18:19]
	s_mov_b32 m0, s14
	ds_read_b128 v[184:187], v150 offset:49152
	ds_read_b128 v[188:191], v150 offset:50176
	ds_read_b128 v[200:203], v150 offset:51200
	ds_read_b128 v[204:207], v150 offset:52224
	ds_read_b128 v[208:211], v150 offset:53248
	ds_read_b128 v[212:215], v150 offset:54272
	ds_read_b128 v[216:219], v150 offset:55296
	ds_read_b128 v[220:223], v150 offset:56320
	global_load_lds_dwordx4 v[148:149], off
	s_add_i32 m0, s14, 0x2000
	v_lshl_add_u64 v[148:149], v[224:225], 0, s[18:19]
	global_load_lds_dwordx4 v[148:149], off
	v_lshl_add_u64 v[148:149], v[226:227], 0, s[18:19]
	s_mov_b32 m0, s52
	s_nop 0
	global_load_lds_dwordx4 v[148:149], off
	v_lshl_add_u64 v[148:149], v[234:235], 0, s[18:19]
	s_mov_b32 m0, s53
	s_nop 0
	global_load_lds_dwordx4 v[148:149], off
	s_waitcnt vmcnt(6)
	s_waitcnt lgkmcnt(0)
	s_cmp_lg_u32 s60, 12
	s_cbranch_scc1 .Lgu_no_ssq_prefetch
	v_lshl_add_u32 v148, s58, 8, v145
	v_ashrrev_i32_e32 v149, 31, v148
	v_lshl_add_u64 v[148:149], v[148:149], 3, s[10:11]
	global_load_dwordx2 v[238:239], v[148:149], off
	global_load_dwordx2 v[240:241], v[148:149], off offset:128
	global_load_dwordx2 v[242:243], v[148:149], off offset:256
	global_load_dwordx2 v[244:245], v[148:149], off offset:384
	global_load_dwordx2 v[246:247], v[148:149], off offset:1024
	global_load_dwordx2 v[248:249], v[148:149], off offset:1152
	global_load_dwordx2 v[250:251], v[148:149], off offset:1280
	global_load_dwordx2 v[228:229], v[148:149], off offset:1408
.Lgu_no_ssq_prefetch:
	s_setprio 1
	s_barrier
	v_mfma_f32_16x16x32_bf16 v[60:63], v[152:155], v[184:187], v[60:63]
	v_mfma_f32_16x16x32_bf16 v[48:51], v[160:163], v[184:187], v[48:51]
	v_mfma_f32_16x16x32_bf16 v[44:47], v[152:155], v[200:203], v[44:47]
	v_mfma_f32_16x16x32_bf16 v[32:35], v[160:163], v[200:203], v[32:35]
	v_mfma_f32_16x16x32_bf16 v[28:31], v[152:155], v[208:211], v[28:31]
	v_mfma_f32_16x16x32_bf16 v[16:19], v[160:163], v[208:211], v[16:19]
	v_mfma_f32_16x16x32_bf16 v[12:15], v[152:155], v[216:219], v[12:15]
	v_mfma_f32_16x16x32_bf16 v[4:7], v[160:163], v[216:219], v[4:7]
	v_mfma_f32_16x16x32_bf16 v[60:63], v[156:159], v[188:191], v[60:63]
	v_mfma_f32_16x16x32_bf16 v[48:51], v[164:167], v[188:191], v[48:51]
	v_mfma_f32_16x16x32_bf16 v[44:47], v[156:159], v[204:207], v[44:47]
	v_mfma_f32_16x16x32_bf16 v[32:35], v[164:167], v[204:207], v[32:35]
	v_mfma_f32_16x16x32_bf16 v[28:31], v[156:159], v[212:215], v[28:31]
	v_mfma_f32_16x16x32_bf16 v[16:19], v[164:167], v[212:215], v[16:19]
	v_mfma_f32_16x16x32_bf16 v[12:15], v[156:159], v[220:223], v[12:15]
	v_mfma_f32_16x16x32_bf16 v[4:7], v[164:167], v[220:223], v[4:7]
	v_mfma_f32_16x16x32_bf16 v[56:59], v[168:171], v[184:187], v[56:59]
	v_mfma_f32_16x16x32_bf16 v[52:55], v[176:179], v[184:187], v[52:55]
	v_mfma_f32_16x16x32_bf16 v[40:43], v[168:171], v[200:203], v[40:43]
	v_mfma_f32_16x16x32_bf16 v[36:39], v[176:179], v[200:203], v[36:39]
	v_mfma_f32_16x16x32_bf16 v[24:27], v[168:171], v[208:211], v[24:27]
	v_mfma_f32_16x16x32_bf16 v[20:23], v[176:179], v[208:211], v[20:23]
	v_mfma_f32_16x16x32_bf16 v[8:11], v[168:171], v[216:219], v[8:11]
	v_mfma_f32_16x16x32_bf16 v[0:3], v[176:179], v[216:219], v[0:3]
	v_mfma_f32_16x16x32_bf16 v[56:59], v[172:175], v[188:191], v[56:59]
	v_mfma_f32_16x16x32_bf16 v[52:55], v[180:183], v[188:191], v[52:55]
	v_mfma_f32_16x16x32_bf16 v[40:43], v[172:175], v[204:207], v[40:43]
	v_mfma_f32_16x16x32_bf16 v[36:39], v[180:183], v[204:207], v[36:39]
	v_mfma_f32_16x16x32_bf16 v[24:27], v[172:175], v[212:215], v[24:27]
	v_mfma_f32_16x16x32_bf16 v[20:23], v[180:183], v[212:215], v[20:23]
	v_mfma_f32_16x16x32_bf16 v[8:11], v[172:175], v[220:223], v[8:11]
	v_mfma_f32_16x16x32_bf16 v[0:3], v[180:183], v[220:223], v[0:3]
	s_setprio 0
	s_barrier
	s_add_i32 s60, s60, 2
	s_add_u32 s46, s46, 0x100
	s_addc_u32 s47, s47, 0
	s_add_u32 s6, s6, 0x100
	s_addc_u32 s7, s7, 0
	s_cmp_gt_u32 s60, 13
	s_cbranch_scc0 .LBB0_128
	s_and_b64 vcc, exec, s[20:21]
	s_cbranch_vccz .LBB0_131
	s_barrier
